# GU phase preamble: row-sum loads issued first, first-tile LDS-DMA loads issued before waiting on them; table reduce + workgroup barrier moved after the tile loads
# baseline (speedup 1.0000x reference)
.LBB0_780:
	s_waitcnt vmcnt(0)
	v_mov_b32_e32 v0, v156
	s_cmp_gt_i32 s4, -1
	s_cselect_b64 s[8:9], -1, 0
	v_cmp_gt_i32_e32 vcc, s55, v0
	s_and_b64 s[18:19], s[8:9], vcc
	s_mov_b64 s[100:101], s[18:19]
	s_and_saveexec_b64 s[8:9], s[18:19]
	s_cbranch_execz .LBB0_782
	v_mov_b32_e32 v118, v156
	v_lshl_add_u32 v100, s4, 8, v118
	v_ashrrev_i32_e32 v101, 31, v100
	v_lshlrev_b64 v[100:101], 6, v[100:101]
	v_lshl_add_u64 v[112:113], s[94:95], 0, v[100:101]
	global_load_dwordx4 v[100:103], v[112:113], off
	global_load_dwordx4 v[104:107], v[112:113], off offset:16
	global_load_dwordx4 v[108:111], v[112:113], off offset:32
	s_nop 0
	global_load_dwordx4 v[112:115], v[112:113], off offset:48
	v_lshl_add_u32 v118, v118, 2, 0
	v_add_u32_e32 v118, 0x20000, v118
.LBB0_782:
	s_or_b64 exec, exec, s[8:9]
	v_mov_b32_e32 v8, v156
	s_cmpk_lt_i32 s0, 0x580
	s_cselect_b64 s[18:19], -1, 0
	s_cmpk_gt_i32 s0, 0x57f
	v_readfirstlane_b32 s14, v8
	s_cbranch_scc1 .LBB0_784
	s_ashr_i32 s8, s0, 31
	s_lshr_b32 s8, s8, 29
	s_add_i32 s8, s0, s8
	s_ashr_i32 s9, s8, 3
	s_and_b32 s8, s8, -8
	s_sub_i32 s8, s0, s8
	s_cmp_lt_i32 s8, 0
	s_movk_i32 s1, 0xb1
	s_cselect_b32 s20, s1, 0xb0
	s_mul_i32 s8, s8, s20
	s_add_i32 s8, s8, s9
	s_mul_hi_i32 s9, s8, 0x2e8ba2e9
	s_lshr_b32 s20, s9, 31
	s_ashr_i32 s9, s9, 5
	s_add_i32 s9, s9, s20
	s_lshl_b32 s20, s9, 3
	s_mulk_i32 s9, 0xb0
	s_sub_i32 s8, s8, s9
	s_bfe_u32 s9, s8, 0x3001c
	s_add_i32 s9, s8, s9
	s_sext_i32_i16 s21, s9
	s_and_b32 s9, s9, 0xfff8
	s_sub_i32 s8, s8, s9
	s_sext_i32_i16 s8, s8
	s_add_i32 s28, s20, s8
	s_ashr_i32 s8, s21, 3
.LBB0_784:
	s_andn2_b64 vcc, exec, s[18:19]
	s_cbranch_vccnz .LBB0_828
	v_ashrrev_i32_e32 v1, 31, v8
	v_lshrrev_b32_e32 v1, 26, v1
	v_add_u32_e32 v1, v8, v1
	v_ashrrev_i32_e32 v9, 6, v1
	v_bfe_i32 v1, v8, 27, 1
	v_lshlrev_b32_e32 v0, 4, v8
	v_lshrrev_b32_e32 v1, 22, v1
	v_add_u32_e32 v1, v0, v1
	v_and_b32_e32 v1, 0xfffffc00, v1
	v_sub_u32_e32 v1, v0, v1
	v_lshrrev_b32_e32 v2, 4, v1
	v_bitop3_b32 v2, v2, v1, 32 bitop3:0x6c
	v_ashrrev_i32_e32 v1, 31, v1
	v_lshrrev_b32_e32 v1, 26, v1
	v_add_u32_e32 v1, v2, v1
	v_ashrrev_i32_e32 v10, 6, v1
	v_lshlrev_b32_e32 v3, 3, v9
	v_mul_i32_i24_e32 v4, 64, v10
	v_and_b32_e32 v3, -16, v3
	v_sub_u32_e32 v2, v2, v4
	v_add_u32_e32 v1, v10, v3
	v_lshlrev_b32_e32 v3, 5, v9
	v_ashrrev_i16_sdwa v2, v192, sext(v2) dst_sel:DWORD dst_unused:UNUSED_PAD src0_sel:DWORD src1_sel:BYTE_0
	v_and_b32_e32 v3, 32, v3
	v_bfe_i32 v11, v2, 0, 16
	v_and_b32_e32 v5, 3, v10
	s_mov_b32 s1, 0x1fffe0
	v_add_lshl_u32 v3, v3, v11, 1
	v_add_u32_e32 v0, 0x2000, v0
	v_lshlrev_b32_e32 v2, 1, v1
	v_lshrrev_b32_e32 v4, 2, v1
	v_and_or_b32 v5, v1, s1, v5
	v_lshl_add_u32 v128, v1, 11, v3
	v_ashrrev_i32_e32 v1, 31, v0
	v_lshrrev_b32_e32 v1, 22, v1
	v_add_u32_e32 v1, v0, v1
	v_ashrrev_i32_e32 v12, 10, v1
	v_mul_i32_i24_e32 v1, 0x400, v12
	v_sub_u32_e32 v0, v0, v1
	v_and_b32_e32 v2, 24, v2
	v_and_b32_e32 v4, 4, v4
	v_lshrrev_b32_e32 v1, 4, v0
	v_or3_b32 v2, v5, v4, v2
	v_bitop3_b32 v0, v1, v0, 32 bitop3:0x6c
	v_lshl_add_u32 v158, v2, 11, v3
	v_ashrrev_i32_e32 v2, 31, v0
	s_ashr_i32 s19, s14, 6
	s_ashr_i32 s18, s14, 8
	v_lshrrev_b32_e32 v2, 26, v2
	s_lshl_b32 s31, s19, 10
	v_add_u32_e32 v2, v0, v2
	s_add_u32 s35, s90, s6
	v_lshlrev_b32_e32 v1, 3, v12
	v_ashrrev_i32_e32 v13, 6, v2
	v_and_b32_e32 v2, 0xc0, v2
	s_addc_u32 s47, s91, s7
	s_ashr_i32 s29, s28, 31
	s_ashr_i32 s9, s8, 31
	v_and_b32_e32 v1, -16, v1
	v_sub_u32_e32 v0, v0, v2
	s_lshl_b64 s[6:7], s[28:29], 19
	s_lshl_b64 s[20:21], s[8:9], 19
	v_add_u32_e32 v1, v13, v1
	v_ashrrev_i16_sdwa v0, v192, sext(v0) dst_sel:DWORD dst_unused:UNUSED_PAD src0_sel:DWORD src1_sel:BYTE_0
	s_add_u32 s62, s35, s20
	v_lshlrev_b32_e32 v3, 5, v12
	v_bfe_i32 v14, v0, 0, 16
	v_lshlrev_b32_e32 v0, 1, v1
	v_lshrrev_b32_e32 v2, 2, v1
	v_and_b32_e32 v4, 3, v13
	s_addc_u32 s63, s47, s21
	s_add_i32 s48, s31, 0
	v_and_b32_e32 v3, 32, v3
	v_and_b32_e32 v0, 24, v0
	v_and_b32_e32 v2, 4, v2
	v_and_or_b32 v4, v1, s1, v4
	s_add_i32 m0, s48, 0x10000
	v_or3_b32 v0, v4, v2, v0
	v_add_lshl_u32 v2, v3, v14, 1
	global_load_lds_dwordx4 v158, s[62:63]
	s_add_i32 m0, s48, 0x12000
	v_lshl_add_u32 v132, v0, 11, v2
	s_add_u32 s58, s96, s6
	global_load_lds_dwordx4 v132, s[62:63]
	s_addc_u32 s59, s97, s7
	s_mov_b32 m0, s48
	s_add_i32 s50, s48, 0x2000
	v_lshl_add_u32 v130, v1, 11, v2
	global_load_lds_dwordx4 v128, s[58:59]
	s_mov_b32 m0, s50
	s_add_u32 s6, s62, 0x40000
	global_load_lds_dwordx4 v130, s[58:59]
	s_addc_u32 s7, s63, 0
	s_add_i32 m0, s48, 0x14000
	v_mov_b32_e32 v133, v159
	global_load_lds_dwordx4 v158, s[6:7]
	s_add_i32 m0, s48, 0x16000
	v_mov_b32_e32 v129, v159
	global_load_lds_dwordx4 v132, s[6:7]
	s_add_u32 s6, s58, 0x40000
	s_addc_u32 s7, s59, 0
	s_add_i32 s65, s48, 0x4000
	s_mov_b32 m0, s65
	s_add_i32 s68, s48, 0x6000
	global_load_lds_dwordx4 v128, s[6:7]
	s_mov_b32 m0, s68
	v_mov_b32_e32 v131, v159
	global_load_lds_dwordx4 v130, s[6:7]
	s_and_saveexec_b64 s[6:7], s[100:101]
	s_cbranch_execz .Lrsov_skip
	s_waitcnt vmcnt(8)
	v_mov_b32_e32 v116, v101
	v_mov_b32_e32 v117, v102
	v_mov_b32_e32 v101, v103
	v_mov_b32_e32 v102, v105
	v_mov_b32_e32 v103, v106
	v_mov_b32_e32 v105, v107
	v_pk_add_f32 v[100:101], v[116:117], v[100:101]
	v_pk_add_f32 v[102:103], v[102:103], v[104:105]
	v_pk_add_f32 v[100:101], v[100:101], v[100:101] op_sel:[0,1] op_sel_hi:[1,0]
	v_pk_add_f32 v[102:103], v[102:103], v[102:103] op_sel:[0,1] op_sel_hi:[1,0]
	v_add_f32_e32 v106, v108, v109
	v_add_f32_e32 v108, v110, v111
	v_mov_b32_e32 v107, v114
	v_mov_b32_e32 v109, v115
	v_mov_b32_e32 v101, v112
	v_mov_b32_e32 v103, v113
	v_pk_add_f32 v[104:105], v[106:107], v[108:109]
	v_pk_add_f32 v[100:101], v[100:101], v[102:103]
	s_nop 0
	v_pk_add_f32 v[100:101], v[100:101], v[104:105]
	s_waitcnt lgkmcnt(0)
	v_add_f32_e32 v119, v100, v101
	v_fmamk_f32 v119, v119, 0x3a800000, v193
	v_mul_f32_e32 v100, 0x4b800000, v119
	v_cmp_gt_f32_e32 vcc, s40, v119
	s_nop 1
	v_cndmask_b32_e32 v119, v119, v100, vcc
	v_rsq_f32_e32 v119, v119
	s_nop 0
	v_mul_f32_e32 v100, 0x45800000, v119
	v_cndmask_b32_e32 v119, v119, v100, vcc
	ds_write_b32 v118, v119
.Lrsov_skip:
	s_or_b64 exec, exec, s[6:7]
	s_waitcnt lgkmcnt(0)
	s_barrier
	v_lshl_add_u64 v[6:7], s[62:63], 0, v[158:159]
	v_lshl_add_u64 v[4:5], s[62:63], 0, v[132:133]
	v_lshl_add_u64 v[2:3], s[58:59], 0, v[128:129]
	s_cmp_lg_u32 s18, 1
	v_lshl_add_u64 v[0:1], s[58:59], 0, v[130:131]
	s_cbranch_scc1 .LBB0_787
	s_barrier
